# 32x32x16 attention loop: next-tile V^T global loads issued right after the K staging writes (one 16-key step earlier)
# baseline (speedup 1.0000x reference)
.Lattn_nf_loop:
	s_and_b32 s10, s15, 1
	s_mul_i32 s6, s10, 0x8800
	v_add_u32_e32 v136, s6, v137
	v_add_u32_e32 v170, s6, v183
	s_sub_u32 s10, 0x8800, s6
	ds_read_b128 v[98:101], v136 offset:0
	ds_read_b128 v[102:105], v136 offset:32
	ds_read_b128 v[106:109], v136 offset:64
	ds_read_b128 v[110:113], v136 offset:96
	v_add_u32_e32 v171, s10, v126
	v_add_u32_e32 v173, s10, v127
	global_load_dwordx4 v[82:85], v124, s[64:65]
	global_load_dwordx4 v[86:89], v124, s[66:67]
	global_load_dwordx4 v[90:93], v124, s[68:69]
	global_load_dwordx4 v[94:97], v124, s[70:71]
	v_add_u32_e32 v124, s36, v124
	s_waitcnt lgkmcnt(3)
	v_mfma_f32_32x32x16_bf16 v[138:153], v[98:101], v[10:13], 0
	ds_read_b128 v[98:101], v136 offset:8704
	s_waitcnt lgkmcnt(3)
	v_mfma_f32_32x32x16_bf16 v[138:153], v[102:105], v[14:17], v[138:153]
	ds_read_b128 v[102:105], v136 offset:8736
	s_waitcnt lgkmcnt(3)
	v_mfma_f32_32x32x16_bf16 v[138:153], v[106:109], v[2:5], v[138:153]
	ds_read_b128 v[106:109], v136 offset:8768
	s_waitcnt lgkmcnt(3)
	v_mfma_f32_32x32x16_bf16 v[138:153], v[110:113], v[6:9], v[138:153]
	ds_read_b128 v[110:113], v136 offset:8800
	ds_read_b128 v[128:131], v170 offset:0
	ds_read_b128 v[184:187], v170 offset:8704
	ds_read_b128 v[188:191], v170 offset:17408
	ds_read_b128 v[192:195], v170 offset:26112
	s_waitcnt lgkmcnt(7)
	v_mfma_f32_32x32x16_bf16 v[154:169], v[98:101], v[10:13], 0
	ds_read_b128 v[98:101], v136 offset:17408
	s_nop 3
	v_exp_f32_e32 v138, v138
	v_exp_f32_e32 v139, v139
	v_exp_f32_e32 v140, v140
	v_exp_f32_e32 v141, v141
	v_exp_f32_e32 v142, v142
	v_exp_f32_e32 v143, v143
	s_waitcnt lgkmcnt(7)
	v_mfma_f32_32x32x16_bf16 v[154:169], v[102:105], v[14:17], v[154:169]
	ds_read_b128 v[102:105], v136 offset:17440
	v_exp_f32_e32 v144, v144
	v_exp_f32_e32 v145, v145
	v_add_f32_e32 v122, v138, v122
	v_add_f32_e32 v122, v139, v122
	v_add_f32_e32 v122, v140, v122
	v_add_f32_e32 v122, v141, v122
	v_add_f32_e32 v122, v142, v122
	v_add_f32_e32 v122, v143, v122
	v_add_f32_e32 v122, v144, v122
	v_add_f32_e32 v122, v145, v122
	v_cvt_pk_bf16_f32 v114, v138, v139
	v_cvt_pk_bf16_f32 v115, v140, v141
	v_cvt_pk_bf16_f32 v116, v142, v143
	v_cvt_pk_bf16_f32 v117, v144, v145
	ds_read_b128 v[196:199], v170 offset:32
	ds_read_b128 v[216:219], v170 offset:8736
	ds_read_b128 v[200:203], v170 offset:17440
	ds_read_b128 v[204:207], v170 offset:26144
	s_waitcnt lgkmcnt(11)
	v_mfma_f32_32x32x16_bf16 v[154:169], v[106:109], v[2:5], v[154:169]
	ds_read_b128 v[106:109], v136 offset:17472
	v_exp_f32_e32 v146, v146
	v_exp_f32_e32 v147, v147
	s_waitcnt lgkmcnt(11)
	v_mfma_f32_32x32x16_bf16 v[154:169], v[110:113], v[6:9], v[154:169]
	ds_read_b128 v[110:113], v136 offset:17504
	v_exp_f32_e32 v148, v148
	v_exp_f32_e32 v149, v149
	s_waitcnt lgkmcnt(11)
	v_mfma_f32_32x32x16_bf16 v[18:33], v[128:131], v[114:117], v[18:33]
	v_exp_f32_e32 v150, v150
	v_exp_f32_e32 v151, v151
	s_waitcnt lgkmcnt(10)
	v_mfma_f32_32x32x16_bf16 v[34:49], v[184:187], v[114:117], v[34:49]
	v_exp_f32_e32 v152, v152
	v_exp_f32_e32 v153, v153
	s_waitcnt lgkmcnt(9)
	v_mfma_f32_32x32x16_bf16 v[50:65], v[188:191], v[114:117], v[50:65]
	v_add_f32_e32 v122, v146, v122
	v_add_f32_e32 v122, v147, v122
	v_add_f32_e32 v122, v148, v122
	v_add_f32_e32 v122, v149, v122
	s_waitcnt lgkmcnt(8)
	v_mfma_f32_32x32x16_bf16 v[66:81], v[192:195], v[114:117], v[66:81]
	v_add_f32_e32 v122, v150, v122
	v_add_f32_e32 v122, v151, v122
	v_add_f32_e32 v122, v152, v122
	v_add_f32_e32 v122, v153, v122
	v_cvt_pk_bf16_f32 v118, v146, v147
	v_cvt_pk_bf16_f32 v119, v148, v149
	v_cvt_pk_bf16_f32 v120, v150, v151
	v_cvt_pk_bf16_f32 v121, v152, v153
	ds_read_b128 v[128:131], v170 offset:64
	ds_read_b128 v[184:187], v170 offset:8768
	ds_read_b128 v[188:191], v170 offset:17472
	ds_read_b128 v[192:195], v170 offset:26176
	s_waitcnt lgkmcnt(11)
	v_mfma_f32_32x32x16_bf16 v[138:153], v[98:101], v[10:13], 0
	ds_read_b128 v[98:101], v136 offset:26112
	v_exp_f32_e32 v154, v154
	v_exp_f32_e32 v155, v155
	s_waitcnt lgkmcnt(11)
	v_mfma_f32_32x32x16_bf16 v[138:153], v[102:105], v[14:17], v[138:153]
	ds_read_b128 v[102:105], v136 offset:26144
	v_exp_f32_e32 v156, v156
	v_exp_f32_e32 v157, v157
	s_waitcnt lgkmcnt(11)
	v_mfma_f32_32x32x16_bf16 v[18:33], v[196:199], v[118:121], v[18:33]
	v_exp_f32_e32 v158, v158
	v_exp_f32_e32 v159, v159
	s_waitcnt lgkmcnt(10)
	v_mfma_f32_32x32x16_bf16 v[34:49], v[216:219], v[118:121], v[34:49]
	v_exp_f32_e32 v160, v160
	v_exp_f32_e32 v161, v161
	s_waitcnt lgkmcnt(9)
	v_mfma_f32_32x32x16_bf16 v[50:65], v[200:203], v[118:121], v[50:65]
	v_add_f32_e32 v122, v154, v122
	v_add_f32_e32 v122, v155, v122
	v_add_f32_e32 v122, v156, v122
	v_add_f32_e32 v122, v157, v122
	s_waitcnt lgkmcnt(8)
	v_mfma_f32_32x32x16_bf16 v[66:81], v[204:207], v[118:121], v[66:81]
	v_add_f32_e32 v122, v158, v122
	v_add_f32_e32 v122, v159, v122
	v_add_f32_e32 v122, v160, v122
	v_add_f32_e32 v122, v161, v122
	v_cvt_pk_bf16_f32 v114, v154, v155
	v_cvt_pk_bf16_f32 v115, v156, v157
	v_cvt_pk_bf16_f32 v116, v158, v159
	v_cvt_pk_bf16_f32 v117, v160, v161
	ds_read_b128 v[196:199], v170 offset:96
	ds_read_b128 v[216:219], v170 offset:8800
	ds_read_b128 v[200:203], v170 offset:17504
	ds_read_b128 v[204:207], v170 offset:26208
	s_waitcnt lgkmcnt(11)
	v_mfma_f32_32x32x16_bf16 v[138:153], v[106:109], v[2:5], v[138:153]
	ds_read_b128 v[106:109], v136 offset:26176
	v_exp_f32_e32 v162, v162
	v_exp_f32_e32 v163, v163
	s_waitcnt lgkmcnt(11)
	v_mfma_f32_32x32x16_bf16 v[138:153], v[110:113], v[6:9], v[138:153]
	ds_read_b128 v[110:113], v136 offset:26208
	v_exp_f32_e32 v164, v164
	v_exp_f32_e32 v165, v165
	s_waitcnt lgkmcnt(11)
	v_mfma_f32_32x32x16_bf16 v[18:33], v[128:131], v[114:117], v[18:33]
	v_exp_f32_e32 v166, v166
	v_exp_f32_e32 v167, v167
	s_waitcnt lgkmcnt(10)
	v_mfma_f32_32x32x16_bf16 v[34:49], v[184:187], v[114:117], v[34:49]
	v_exp_f32_e32 v168, v168
	v_exp_f32_e32 v169, v169
	s_waitcnt lgkmcnt(9)
	v_mfma_f32_32x32x16_bf16 v[50:65], v[188:191], v[114:117], v[50:65]
	v_add_f32_e32 v122, v162, v122
	v_add_f32_e32 v122, v163, v122
	v_add_f32_e32 v122, v164, v122
	v_add_f32_e32 v122, v165, v122
	s_waitcnt lgkmcnt(8)
	v_mfma_f32_32x32x16_bf16 v[66:81], v[192:195], v[114:117], v[66:81]
	v_add_f32_e32 v122, v166, v122
	v_add_f32_e32 v122, v167, v122
	v_add_f32_e32 v122, v168, v122
	v_add_f32_e32 v122, v169, v122
	v_cvt_pk_bf16_f32 v118, v162, v163
	v_cvt_pk_bf16_f32 v119, v164, v165
	v_cvt_pk_bf16_f32 v120, v166, v167
	v_cvt_pk_bf16_f32 v121, v168, v169
	ds_read_b128 v[128:131], v170 offset:128
	ds_read_b128 v[184:187], v170 offset:8832
	ds_read_b128 v[188:191], v170 offset:17536
	ds_read_b128 v[192:195], v170 offset:26240
	s_waitcnt lgkmcnt(11)
	v_mfma_f32_32x32x16_bf16 v[154:169], v[98:101], v[10:13], 0
	v_exp_f32_e32 v138, v138
	s_waitcnt lgkmcnt(10)
	v_mfma_f32_32x32x16_bf16 v[154:169], v[102:105], v[14:17], v[154:169]
	v_exp_f32_e32 v139, v139
	v_exp_f32_e32 v140, v140
	s_waitcnt lgkmcnt(9)
	v_mfma_f32_32x32x16_bf16 v[18:33], v[196:199], v[118:121], v[18:33]
	v_exp_f32_e32 v141, v141
	s_waitcnt vmcnt(3)
	ds_write_b128 v171, v[82:85] offset:0
	s_waitcnt vmcnt(2)
	ds_write_b128 v171, v[86:89] offset:8704
	s_waitcnt vmcnt(1)
	ds_write_b128 v171, v[90:93] offset:17408
	s_waitcnt vmcnt(0)
	ds_write_b128 v171, v[94:97] offset:26112
	v_exp_f32_e32 v142, v142
	v_exp_f32_e32 v143, v143
	s_waitcnt lgkmcnt(12)
	v_mfma_f32_32x32x16_bf16 v[34:49], v[216:219], v[118:121], v[34:49]
	v_exp_f32_e32 v144, v144
	global_load_dwordx4 v[82:85], v125, s[72:73]
	global_load_dwordx4 v[86:89], v125, s[74:75]
	global_load_dwordx4 v[90:93], v125, s[76:77]
	global_load_dwordx4 v[94:97], v125, s[78:79]
	v_add_u32_e32 v125, s38, v125
	v_exp_f32_e32 v145, v145
	v_add_f32_e32 v122, v138, v122
	v_add_f32_e32 v122, v139, v122
	s_waitcnt lgkmcnt(11)
	v_mfma_f32_32x32x16_bf16 v[50:65], v[200:203], v[118:121], v[50:65]
	v_add_f32_e32 v122, v140, v122
	v_add_f32_e32 v122, v141, v122
	v_add_f32_e32 v122, v142, v122
	s_waitcnt lgkmcnt(10)
	v_mfma_f32_32x32x16_bf16 v[66:81], v[204:207], v[118:121], v[66:81]
	v_add_f32_e32 v122, v143, v122
	v_add_f32_e32 v122, v144, v122
	v_add_f32_e32 v122, v145, v122
	v_cvt_pk_bf16_f32 v114, v138, v139
	v_cvt_pk_bf16_f32 v115, v140, v141
	v_cvt_pk_bf16_f32 v116, v142, v143
	v_cvt_pk_bf16_f32 v117, v144, v145
	ds_read_b128 v[196:199], v170 offset:160
	ds_read_b128 v[216:219], v170 offset:8864
	ds_read_b128 v[200:203], v170 offset:17568
	ds_read_b128 v[204:207], v170 offset:26272
	s_waitcnt lgkmcnt(13)
	v_mfma_f32_32x32x16_bf16 v[154:169], v[106:109], v[2:5], v[154:169]
	v_exp_f32_e32 v146, v146
	v_exp_f32_e32 v147, v147
	s_waitcnt lgkmcnt(12)
	v_mfma_f32_32x32x16_bf16 v[154:169], v[110:113], v[6:9], v[154:169]
	v_exp_f32_e32 v148, v148
	v_exp_f32_e32 v149, v149
	s_waitcnt lgkmcnt(11)
	v_mfma_f32_32x32x16_bf16 v[18:33], v[128:131], v[114:117], v[18:33]
	v_exp_f32_e32 v150, v150
	v_exp_f32_e32 v151, v151
	s_waitcnt lgkmcnt(10)
	v_mfma_f32_32x32x16_bf16 v[34:49], v[184:187], v[114:117], v[34:49]
	v_exp_f32_e32 v152, v152
	v_exp_f32_e32 v153, v153
	s_waitcnt lgkmcnt(9)
	v_mfma_f32_32x32x16_bf16 v[50:65], v[188:191], v[114:117], v[50:65]
	v_add_f32_e32 v122, v146, v122
	v_add_f32_e32 v122, v147, v122
	v_add_f32_e32 v122, v148, v122
	v_add_f32_e32 v122, v149, v122
	s_waitcnt lgkmcnt(8)
	v_mfma_f32_32x32x16_bf16 v[66:81], v[192:195], v[114:117], v[66:81]
	v_add_f32_e32 v122, v150, v122
	v_add_f32_e32 v122, v151, v122
	v_add_f32_e32 v122, v152, v122
	v_add_f32_e32 v122, v153, v122
	v_cvt_pk_bf16_f32 v118, v146, v147
	v_cvt_pk_bf16_f32 v119, v148, v149
	v_cvt_pk_bf16_f32 v120, v150, v151
	v_cvt_pk_bf16_f32 v121, v152, v153
	ds_read_b128 v[128:131], v170 offset:192
	ds_read_b128 v[184:187], v170 offset:8896
	ds_read_b128 v[188:191], v170 offset:17600
	ds_read_b128 v[192:195], v170 offset:26304
	s_waitcnt lgkmcnt(7)
	v_mfma_f32_32x32x16_bf16 v[18:33], v[196:199], v[118:121], v[18:33]
	v_exp_f32_e32 v154, v154
	v_exp_f32_e32 v155, v155
	v_exp_f32_e32 v156, v156
	s_waitcnt lgkmcnt(6)
	v_mfma_f32_32x32x16_bf16 v[34:49], v[216:219], v[118:121], v[34:49]
	v_exp_f32_e32 v157, v157
	v_exp_f32_e32 v158, v158
	v_exp_f32_e32 v159, v159
	s_waitcnt lgkmcnt(5)
	v_mfma_f32_32x32x16_bf16 v[50:65], v[200:203], v[118:121], v[50:65]
	v_exp_f32_e32 v160, v160
	v_exp_f32_e32 v161, v161
	v_add_f32_e32 v122, v154, v122
	v_add_f32_e32 v122, v155, v122
	s_waitcnt lgkmcnt(4)
	v_mfma_f32_32x32x16_bf16 v[66:81], v[204:207], v[118:121], v[66:81]
	v_add_f32_e32 v122, v156, v122
	v_add_f32_e32 v122, v157, v122
	v_add_f32_e32 v122, v158, v122
	v_add_f32_e32 v122, v159, v122
	v_add_f32_e32 v122, v160, v122
	v_add_f32_e32 v122, v161, v122
	v_cvt_pk_bf16_f32 v114, v154, v155
	v_cvt_pk_bf16_f32 v115, v156, v157
	v_cvt_pk_bf16_f32 v116, v158, v159
	v_cvt_pk_bf16_f32 v117, v160, v161
	ds_read_b128 v[196:199], v170 offset:224
	ds_read_b128 v[216:219], v170 offset:8928
	ds_read_b128 v[200:203], v170 offset:17632
	ds_read_b128 v[204:207], v170 offset:26336
	s_waitcnt lgkmcnt(7)
	v_mfma_f32_32x32x16_bf16 v[18:33], v[128:131], v[114:117], v[18:33]
	v_exp_f32_e32 v162, v162
	v_exp_f32_e32 v163, v163
	v_exp_f32_e32 v164, v164
	s_waitcnt lgkmcnt(6)
	v_mfma_f32_32x32x16_bf16 v[34:49], v[184:187], v[114:117], v[34:49]
	v_exp_f32_e32 v165, v165
	v_exp_f32_e32 v166, v166
	v_exp_f32_e32 v167, v167
	s_waitcnt lgkmcnt(5)
	v_mfma_f32_32x32x16_bf16 v[50:65], v[188:191], v[114:117], v[50:65]
	v_exp_f32_e32 v168, v168
	v_exp_f32_e32 v169, v169
	v_add_f32_e32 v122, v162, v122
	v_add_f32_e32 v122, v163, v122
	s_waitcnt lgkmcnt(4)
	v_mfma_f32_32x32x16_bf16 v[66:81], v[192:195], v[114:117], v[66:81]
	v_add_f32_e32 v122, v164, v122
	v_add_f32_e32 v122, v165, v122
	v_add_f32_e32 v122, v166, v122
	v_add_f32_e32 v122, v167, v122
	v_add_f32_e32 v122, v168, v122
	v_add_f32_e32 v122, v169, v122
	v_cvt_pk_bf16_f32 v118, v162, v163
	v_cvt_pk_bf16_f32 v119, v164, v165
	v_cvt_pk_bf16_f32 v120, v166, v167
	v_cvt_pk_bf16_f32 v121, v168, v169
	s_waitcnt lgkmcnt(3)
	s_nop 0
	v_mfma_f32_32x32x16_bf16 v[18:33], v[196:199], v[118:121], v[18:33]
	s_waitcnt lgkmcnt(2)
	v_mfma_f32_32x32x16_bf16 v[34:49], v[216:219], v[118:121], v[34:49]
	s_waitcnt vmcnt(3)
	ds_write_b128 v173, v[82:85] offset:0
	s_waitcnt vmcnt(2)
	ds_write_b128 v173, v[86:89] offset:8704
	s_waitcnt vmcnt(1)
	ds_write_b128 v173, v[90:93] offset:17408
	s_waitcnt vmcnt(0)
	ds_write_b128 v173, v[94:97] offset:26112
	s_waitcnt lgkmcnt(5)
	v_mfma_f32_32x32x16_bf16 v[50:65], v[200:203], v[118:121], v[50:65]
	s_waitcnt lgkmcnt(4)
	v_mfma_f32_32x32x16_bf16 v[66:81], v[204:207], v[118:121], v[66:81]
	s_waitcnt lgkmcnt(0)
	s_barrier
	s_add_i32 s15, s15, 1
	s_cmp_eq_u32 s15, 34
	s_cbranch_scc0 .Lattn_nf_loop
	v_readlane_b32 s64, v175, 0
	v_readlane_b32 s65, v175, 1
	v_readlane_b32 s66, v175, 2
	v_readlane_b32 s67, v175, 3
	v_readlane_b32 s68, v175, 4
	v_readlane_b32 s69, v175, 5
	v_readlane_b32 s70, v175, 6
	v_readlane_b32 s71, v175, 7
	v_readlane_b32 s72, v175, 8
	v_readlane_b32 s73, v175, 9
	v_readlane_b32 s74, v175, 10
	v_readlane_b32 s75, v175, 11
	v_readlane_b32 s76, v175, 12
	v_readlane_b32 s77, v175, 13
	v_readlane_b32 s78, v175, 14
	v_readlane_b32 s79, v175, 15
	s_nop 4
	v_add_f32_e32 v186, v132, v134
	v_add_f32_e32 v184, v133, v135
	ds_bpermute_b32 v187, v172, v186
	ds_bpermute_b32 v185, v172, v184
	s_mov_b32 s10, 0x3fb8aa3b
	s_mov_b32 s11, 0xc2ce8ed0
	s_mov_b32 s6, 0x42b17218
	v_cmp_eq_u32_e64 s[40:41], 0, v179
	s_lshl_b32 s30, s14, 1
	v_lshlrev_b32_e32 v196, 3, v178
	v_mov_b32_e32 v197, 0
	v_lshlrev_b32_e32 v198, 4, v179
	v_or3_b32 v198, v198, v177, v180
	v_ashrrev_i32_e32 v199, 31, v198
	v_lshlrev_b64 v[198:199], 11, v[198:199]
	s_mov_b64 s[100:101], 0x18a10000
	v_lshl_add_u64 v[198:199], s[42:43], 0, v[198:199]
	v_lshl_add_u64 v[198:199], v[198:199], 0, s[30:31]
	v_lshl_add_u64 v[198:199], v[198:199], 0, v[196:197]
	v_lshl_add_u64 v[198:199], v[198:199], 0, s[100:101]
	global_load_dwordx2 v[146:147], v[198:199], off
	global_load_dwordx2 v[148:149], v[198:199], off offset:32
	global_load_dwordx2 v[150:151], v[198:199], off offset:64
	global_load_dwordx2 v[152:153], v[198:199], off offset:96
	global_load_dwordx2 v[188:189], v[198:199], off offset:128
	global_load_dwordx2 v[190:191], v[198:199], off offset:160
	global_load_dwordx2 v[192:193], v[198:199], off offset:192
	global_load_dwordx2 v[194:195], v[198:199], off offset:224
	s_mov_b64 s[100:101], exec
	s_and_b64 exec, exec, s[4:5]
	s_cbranch_execz .Lpop_skip
	v_readlane_b32 s14, v255, 22
	v_readlane_b32 s15, v255, 23
	v_mov_b32_e32 v224, 1
	s_nop 4
	global_atomic_add v224, v0, v224, s[14:15] sc0
